# P1 unit order: odd rounds swap workgroup w with w^16 so each workgroup gets two light and two heavy epilogue tiles (on top of the P2/P4 rebalance)
# baseline (speedup 1.0000x reference)
.LBB0_106:
	s_add_i32 s23, s23, 1
	s_cmp_ge_u32 s23, s33
	s_mov_b64 s[50:51], 0
	s_cbranch_scc1 .LBB0_119
	s_mul_i32 s1, s23, s89
	s_add_i32 s1, s1, s88
	s_cmpk_gt_i32 s1, 0x43f
	s_cbranch_scc1 .LBB0_119
	s_and_b32 s2, s1, 7
	s_mulk_i32 s2, 0x88
	s_ashr_i32 s1, s1, 3
	s_bfe_u32 s100, s1, 0x10005
	s_lshl_b32 s100, s100, 4
	s_xor_b32 s1, s1, s100
	s_and_b64 vcc, exec, s[60:61]
	s_add_i32 s1, s2, s1
	s_cbranch_vccnz .LBB0_114
	s_and_b32 s2, s1, -8
	s_cmpk_lg_i32 s2, 0x400
	s_mov_b64 s[2:3], -1
	s_cbranch_scc0 .LBB0_111
	s_sub_i32 s2, s1, 56
	s_cmpk_gt_i32 s1, 0x437
	s_cselect_b32 s9, s2, s1
	s_mov_b64 s[2:3], 0
